# scan chunk body hand-rewritten: operands prefetched 2 steps ahead with counted lgkmcnt, y reduce-scatter per chunk, scan at prio 0
# speedup vs baseline: 1.0074x; 1.0074x over previous
; #define LAUNDER_IDS const int tid__ = launder_v((int)threadIdx.x); const int blk__ = launder_s((int)blockIdx.x); (void)tid__; (void)blk__;
; DI void phase_scan(const Params& p, char* smem) {
;   LAUNDER_IDS
;   const int blk = blk__;
;   if (blk >= 256) return;
;   const int tid = tid__, lane = tid & 63, wave = tid >> 6, kq = lane & 15, rg = lane >> 4;
;   const int chain = (blk & 7) + 8 * (blk >> 5), quarter = (blk >> 3) & 3;
;   const int b = chain >> 3, h = (chain >> 1) & 3, dir = chain & 1;
;   const u16* sc = (const u16*)(p.ws + OFF_R3);
;   const size_t AS = (size_t)NT * 256;
;   const u16* aOMW = sc + (dir ? SA_OMWB : SA_OMWF) * AS;
;   const u16* aKD = sc + (dir ? SA_KDB : SA_KDF) * AS;
;   const u16* aB = sc + (dir ? SA_BB : SA_BF) * AS;
;   const u16* aKKN = sc + SA_KKN * AS;
;   const u16* aR = sc + SA_R * AS;
;   const u16* aV = sc + SA_V * AS;
;   u16* Y = (u16*)(p.ws + OFF_R2) + (dir ? AS : 0);
;   constexpr int CH = 16, BSZ = 5 * CH * 64 + CH * 16;
;   float* buf = (float*)smem;
;   const int st_ld = tid >> 4, k4 = (tid & 15) * 4;
;   const int vrow = quarter * 16 + wave * 4 + rg;
;   uint2 g0, g1, g2, g3, g4; u16 gv;
;     ...
;   float2_t S01 = {0.f, 0.f}, S23 = {0.f, 0.f};
;   __builtin_amdgcn_s_setprio(3);
;   __syncthreads();
;   SCAN_GLOAD(0); SCAN_LSTORE(0);
; __global__ void __launch_bounds__(256, 2) fwd_megakernel(Params pk) {
;     ...
;     switch (q) {
;       case 0: phase_norm(XLP, XCP, TABP(0), (u16*)(p.ws + OFF_HB1), NT); break;
;       case 1: phase_zgemm(p, l, smem); break;
;       case 2: phase_tokA(p, l); phase_tokB(p, l, smem); break;
;       case 3: phase_qkv(p, l, smem); break;
;       case 4: phase_scan(p, smem); phase_attn(p, l, smem); break;
.LBB0_497:
	s_and_b64 vcc, exec, s[4:5]
	s_cbranch_vccz .LBB0_958
	v_readlane_b32 s0, v253, 36
	s_cmp_gt_i32 s0, 1
	s_mov_b64 s[0:1], -1
	s_cbranch_scc0 .LBB0_848
	v_readlane_b32 s0, v253, 36
	s_cmp_lt_i32 s0, 3
	s_mov_b64 s[0:1], -1
	s_cbranch_scc1 .LBB0_754
	v_readlane_b32 s0, v253, 36
	s_cmp_gt_i32 s0, 3
	s_mov_b64 s[0:1], -1
	s_cbranch_scc0 .LBB0_542
	v_mov_b32_e32 v14, v163
	s_mov_b32 s6, s2
	s_cmpk_gt_i32 s6, 0xff
	s_cbranch_scc1 .LBB0_517
	s_ashr_i32 s8, s6, 5
	s_and_b32 s7, s6, 1
	s_cmp_eq_u32 s7, 0
	s_cselect_b64 s[0:1], -1, 0
	v_ashrrev_i32_e32 v3, 4, v14
	s_setprio 0
	s_movk_i32 s4, 0xff
	v_cmp_lt_i32_e32 vcc, s4, v3
	s_waitcnt lgkmcnt(0)
	s_barrier
	s_and_saveexec_b64 s[4:5], vcc
	s_xor_b64 s[4:5], exec, s[4:5]
	s_cbranch_execz .LBB0_504
	v_add_u32_e32 v0, 0xffffff00, v3
	v_sub_u32_e32 v2, 0x10ff, v3
	s_lshl_b32 s10, s8, 8
	s_lshl_b32 s9, s8, 12
	v_cndmask_b32_e64 v0, v2, v0, s[0:1]
	s_add_i32 s10, s10, 0x8000
	s_waitcnt vmcnt(0)
	v_add_u32_e32 v4, s9, v0
	v_mov_b32_e32 v22, s10
	v_mov_b32_e32 v23, s9

; DI void phase_scan(const Params& p, char* smem) {
;     ...
;   for (int c = 0; c < NCH; ++c) {
;     if (c + 1 < NCH) SCAN_GLOAD(c + 1);
;     const float* bb = buf + (c & 1) * BSZ;
;     const int rowbase = scan_row(b, dir, c * CH);
;     const int rstep = dir ? -1 : 1;
;     const float* bl = bb + kq * 4;
;     const float* bv = bb + 5 * CH * 64 + wave * 4 + rg;
;     float4 fwv[3], fkv[3], fbv[3], fav[3], frv[3]; float vvv[3];
; #pragma unroll
;     for (int q = 0; q < 2; ++q) {
;       fwv[q] = *(const float4*)(bl + 0 * CH * 64 + q * 64); fkv[q] = *(const float4*)(bl + 1 * CH * 64 + q * 64); fbv[q] = *(const float4*)(bl + 2 * CH * 64 + q * 64);
;       fav[q] = *(const float4*)(bl + 3 * CH * 64 + q * 64); frv[q] = *(const float4*)(bl + 4 * CH * 64 + q * 64); vvv[q] = bv[q * 16];
;     }
;     float ysel = 0.f, ypart = 0.f;
; #pragma unroll
;     for (int s = 0; s < CH; ++s) {
;       const float4 fw = fwv[s % 3], fk = fkv[s % 3], fb = fbv[s % 3], fa = fav[s % 3], fr = frv[s % 3];
;       const float vv = vvv[s % 3];
;       const float2_t a01 = {fa.x, fa.y}, a23 = {fa.z, fa.w};
;       const float2_t w01 = {fw.x, fw.y}, w23 = {fw.z, fw.w}, k01 = {fk.x, fk.y}, k23 = {fk.z, fk.w}, b01 = {fb.x, fb.y}, b23 = {fb.z, fb.w};
;       const float2_t r01 = {fr.x, fr.y}, r23 = {fr.z, fr.w};
;       const float2_t vv2 = {vv, vv};
;       if (s + 2 < CH) {
;         constexpr int dummy = 0; (void)dummy;
;         const int q = (s + 2) % 3;
;         fwv[q] = *(const float4*)(bl + 0 * CH * 64 + (s + 2) * 64); fkv[q] = *(const float4*)(bl + 1 * CH * 64 + (s + 2) * 64); fbv[q] = *(const float4*)(bl + 2 * CH * 64 + (s + 2) * 64);
;         fav[q] = *(const float4*)(bl + 3 * CH * 64 + (s + 2) * 64); frv[q] = *(const float4*)(bl + 4 * CH * 64 + (s + 2) * 64); vvv[q] = bv[(s + 2) * 16];
;       }
;       float2_t t2 = S01 * a01; t2 = S23 * a23 + t2;
;       const float2_t q01 = S01 * w01 + vv2 * k01, q23 = S23 * w23 + vv2 * k23;
;       float xs = t2.x + t2.y, ys = ypart;
;       xs += __builtin_bit_cast(float, __builtin_amdgcn_update_dpp(0, __builtin_bit_cast(int, xs), 0x128, 0xf, 0xf, false));
;       ys += __builtin_bit_cast(float, __builtin_amdgcn_update_dpp(0, __builtin_bit_cast(int, ys), 0x128, 0xf, 0xf, false));
;       xs += __builtin_bit_cast(float, __builtin_amdgcn_update_dpp(0, __builtin_bit_cast(int, xs), 0x124, 0xf, 0xf, false));
.LBB0_512:
	s_bitcmp1_b32 s96, 0
	s_cselect_b32 s79, 0x5400, 0
	v_lshlrev_b32_e32 v32, 2, v25
	v_lshlrev_b32_e32 v33, 2, v24
	v_add3_u32 v32, s79, v32, v33
	v_add_u32_e32 v32, 0x5000, v32
	v_lshl_or_b32 v31, v2, 2, s79
	ds_read2_b32 v[164:165], v32 offset0:0 offset1:16
	ds_read2_b32 v[166:167], v32 offset0:32 offset1:48
	ds_read2_b32 v[168:169], v32 offset0:64 offset1:80
	ds_read2_b32 v[170:171], v32 offset0:96 offset1:112
	ds_read_b128 v[100:103], v31 offset:0
	ds_read_b128 v[104:107], v31 offset:4096
	ds_read_b128 v[108:111], v31 offset:8192
	ds_read_b128 v[112:115], v31 offset:12288
	ds_read_b128 v[116:119], v31 offset:16384
	ds_read_b128 v[120:123], v31 offset:256
	ds_read_b128 v[124:127], v31 offset:4352
	ds_read_b128 v[128:131], v31 offset:8448
	ds_read_b128 v[132:135], v31 offset:12544
	ds_read_b128 v[136:139], v31 offset:16640
	v_add_u32_e32 v30, v30, v0
	s_add_i32 s96, s96, 1
	s_andn2_b64 vcc, exec, s[46:47]
	s_waitcnt lgkmcnt(5)
	v_pk_mul_f32 v[42:43], v[114:115], v[20:21]
	v_pk_mul_f32 v[46:47], v[102:103], v[20:21]
	v_pk_fma_f32 v[42:43], v[112:113], v[18:19], v[42:43]
	v_pk_mul_f32 v[44:45], v[100:101], v[18:19]
	v_add_f32_e32 v48, v42, v43
	v_pk_fma_f32 v[44:45], v[104:105], v[164:165], v[44:45] op_sel_hi:[1,0,1]
	v_pk_fma_f32 v[46:47], v[106:107], v[164:165], v[46:47] op_sel_hi:[1,0,1]
	v_add_f32_dpp v48, v48, v48 row_ror:8 row_mask:0xf bank_mask:0xf bound_ctrl:1
	ds_read_b128 v[140:143], v31 offset:512
	ds_read_b128 v[144:147], v31 offset:4608
	v_add_f32_dpp v48, v48, v48 row_ror:4 row_mask:0xf bank_mask:0xf bound_ctrl:1
	ds_read_b128 v[148:151], v31 offset:8704
	ds_read_b128 v[152:155], v31 offset:12800
	v_add_f32_dpp v48, v48, v48 row_ror:2 row_mask:0xf bank_mask:0xf bound_ctrl:1
	ds_read_b128 v[156:159], v31 offset:16896
	s_nop 0
	v_add_f32_dpp v48, v48, v48 row_ror:1 row_mask:0xf bank_mask:0xf bound_ctrl:1
	v_pk_fma_f32 v[18:19], v[108:109], v[48:49], v[44:45] op_sel_hi:[1,0,1]
	v_pk_fma_f32 v[20:21], v[110:111], v[48:49], v[46:47] op_sel_hi:[1,0,1]
	s_waitcnt lgkmcnt(5)
	v_pk_mul_f32 v[42:43], v[134:135], v[20:21]
	v_pk_mul_f32 v[46:47], v[122:123], v[20:21]
	v_pk_fma_f32 v[42:43], v[132:133], v[18:19], v[42:43]
	v_pk_mul_f32 v[44:45], v[120:121], v[18:19]
	v_add_f32_e32 v48, v42, v43
	v_pk_fma_f32 v[44:45], v[124:125], v[164:165], v[44:45] op_sel:[0,1,0]
	v_pk_fma_f32 v[46:47], v[126:127], v[164:165], v[46:47] op_sel:[0,1,0]
	v_add_f32_dpp v48, v48, v48 row_ror:8 row_mask:0xf bank_mask:0xf bound_ctrl:1
	v_pk_mul_f32 v[50:51], v[116:117], v[18:19]
	v_pk_fma_f32 v[50:51], v[118:119], v[20:21], v[50:51]
	v_add_f32_dpp v48, v48, v48 row_ror:4 row_mask:0xf bank_mask:0xf bound_ctrl:1
	v_add_f32_e32 v180, v50, v51
	ds_read_b128 v[100:103], v31 offset:768
	v_add_f32_dpp v48, v48, v48 row_ror:2 row_mask:0xf bank_mask:0xf bound_ctrl:1
	ds_read_b128 v[104:107], v31 offset:4864
	ds_read_b128 v[108:111], v31 offset:8960
	v_add_f32_dpp v48, v48, v48 row_ror:1 row_mask:0xf bank_mask:0xf bound_ctrl:1
	ds_read_b128 v[112:115], v31 offset:13056
	ds_read_b128 v[116:119], v31 offset:17152
	v_pk_fma_f32 v[18:19], v[128:129], v[48:49], v[44:45] op_sel_hi:[1,0,1]
	v_pk_fma_f32 v[20:21], v[130:131], v[48:49], v[46:47] op_sel_hi:[1,0,1]
	s_waitcnt lgkmcnt(5)
	v_pk_mul_f32 v[42:43], v[154:155], v[20:21]
	v_pk_mul_f32 v[46:47], v[142:143], v[20:21]
	v_pk_fma_f32 v[42:43], v[152:153], v[18:19], v[42:43]
	v_pk_mul_f32 v[44:45], v[140:141], v[18:19]
	v_add_f32_e32 v48, v42, v43
	v_pk_fma_f32 v[44:45], v[144:145], v[166:167], v[44:45] op_sel_hi:[1,0,1]
	v_pk_fma_f32 v[46:47], v[146:147], v[166:167], v[46:47] op_sel_hi:[1,0,1]
	v_add_f32_dpp v48, v48, v48 row_ror:8 row_mask:0xf bank_mask:0xf bound_ctrl:1
	v_pk_mul_f32 v[50:51], v[136:137], v[18:19]
	v_pk_fma_f32 v[50:51], v[138:139], v[20:21], v[50:51]
	v_add_f32_dpp v48, v48, v48 row_ror:4 row_mask:0xf bank_mask:0xf bound_ctrl:1
	v_add_f32_e32 v181, v50, v51
	ds_read_b128 v[120:123], v31 offset:1024
	v_add_f32_dpp v48, v48, v48 row_ror:2 row_mask:0xf bank_mask:0xf bound_ctrl:1
	ds_read_b128 v[124:127], v31 offset:5120
	ds_read_b128 v[128:131], v31 offset:9216
	v_add_f32_dpp v48, v48, v48 row_ror:1 row_mask:0xf bank_mask:0xf bound_ctrl:1
	ds_read_b128 v[132:135], v31 offset:13312
	ds_read_b128 v[136:139], v31 offset:17408
	ds_read2_b32 v[172:173], v32 offset0:128 offset1:144
	ds_read2_b32 v[174:175], v32 offset0:160 offset1:176
	v_pk_fma_f32 v[18:19], v[148:149], v[48:49], v[44:45] op_sel_hi:[1,0,1]
	v_pk_fma_f32 v[20:21], v[150:151], v[48:49], v[46:47] op_sel_hi:[1,0,1]
	s_waitcnt lgkmcnt(7)
	v_pk_mul_f32 v[42:43], v[114:115], v[20:21]
	v_pk_mul_f32 v[46:47], v[102:103], v[20:21]
	v_pk_fma_f32 v[42:43], v[112:113], v[18:19], v[42:43]
	v_pk_mul_f32 v[44:45], v[100:101], v[18:19]
	v_add_f32_e32 v48, v42, v43
	v_pk_fma_f32 v[44:45], v[104:105], v[166:167], v[44:45] op_sel:[0,1,0]
	v_pk_fma_f32 v[46:47], v[106:107], v[166:167], v[46:47] op_sel:[0,1,0]
	v_add_f32_dpp v48, v48, v48 row_ror:8 row_mask:0xf bank_mask:0xf bound_ctrl:1
	v_pk_mul_f32 v[50:51], v[156:157], v[18:19]
	v_pk_fma_f32 v[50:51], v[158:159], v[20:21], v[50:51]
	v_add_f32_dpp v48, v48, v48 row_ror:4 row_mask:0xf bank_mask:0xf bound_ctrl:1
	v_add_f32_e32 v182, v50, v51
	ds_read_b128 v[140:143], v31 offset:1280
	v_add_f32_dpp v48, v48, v48 row_ror:2 row_mask:0xf bank_mask:0xf bound_ctrl:1
	ds_read_b128 v[144:147], v31 offset:5376
	ds_read_b128 v[148:151], v31 offset:9472
	v_add_f32_dpp v48, v48, v48 row_ror:1 row_mask:0xf bank_mask:0xf bound_ctrl:1
	ds_read_b128 v[152:155], v31 offset:13568
	ds_read_b128 v[156:159], v31 offset:17664
	ds_read2_b32 v[176:177], v32 offset0:192 offset1:208
	ds_read2_b32 v[178:179], v32 offset0:224 offset1:240
	v_pk_fma_f32 v[18:19], v[108:109], v[48:49], v[44:45] op_sel_hi:[1,0,1]
	v_pk_fma_f32 v[20:21], v[110:111], v[48:49], v[46:47] op_sel_hi:[1,0,1]
	s_waitcnt lgkmcnt(9)
; DI void phase_scan(const Params& p, char* smem) {
;     ...
;       const float4 fw = fwv[s % 3], fk = fkv[s % 3], fb = fbv[s % 3], fa = fav[s % 3], fr = frv[s % 3];
;       const float vv = vvv[s % 3];
;       const float2_t a01 = {fa.x, fa.y}, a23 = {fa.z, fa.w};
;       const float2_t w01 = {fw.x, fw.y}, w23 = {fw.z, fw.w}, k01 = {fk.x, fk.y}, k23 = {fk.z, fk.w}, b01 = {fb.x, fb.y}, b23 = {fb.z, fb.w};
;       const float2_t r01 = {fr.x, fr.y}, r23 = {fr.z, fr.w};
;       const float2_t vv2 = {vv, vv};
;       if (s + 2 < CH) {
;         constexpr int dummy = 0; (void)dummy;
;         const int q = (s + 2) % 3;
;         fwv[q] = *(const float4*)(bl + 0 * CH * 64 + (s + 2) * 64); fkv[q] = *(const float4*)(bl + 1 * CH * 64 + (s + 2) * 64); fbv[q] = *(const float4*)(bl + 2 * CH * 64 + (s + 2) * 64);
;         fav[q] = *(const float4*)(bl + 3 * CH * 64 + (s + 2) * 64); frv[q] = *(const float4*)(bl + 4 * CH * 64 + (s + 2) * 64); vvv[q] = bv[(s + 2) * 16];
;       }
;       float2_t t2 = S01 * a01; t2 = S23 * a23 + t2;
;       const float2_t q01 = S01 * w01 + vv2 * k01, q23 = S23 * w23 + vv2 * k23;
;       float xs = t2.x + t2.y, ys = ypart;
;       xs += __builtin_bit_cast(float, __builtin_amdgcn_update_dpp(0, __builtin_bit_cast(int, xs), 0x128, 0xf, 0xf, false));
;       ys += __builtin_bit_cast(float, __builtin_amdgcn_update_dpp(0, __builtin_bit_cast(int, ys), 0x128, 0xf, 0xf, false));
;       xs += __builtin_bit_cast(float, __builtin_amdgcn_update_dpp(0, __builtin_bit_cast(int, xs), 0x124, 0xf, 0xf, false));
;       ys += __builtin_bit_cast(float, __builtin_amdgcn_update_dpp(0, __builtin_bit_cast(int, ys), 0x124, 0xf, 0xf, false));
;       xs += __builtin_bit_cast(float, __builtin_amdgcn_update_dpp(0, __builtin_bit_cast(int, xs), 0x122, 0xf, 0xf, false));
;       ys += __builtin_bit_cast(float, __builtin_amdgcn_update_dpp(0, __builtin_bit_cast(int, ys), 0x122, 0xf, 0xf, false));
;       xs += __builtin_bit_cast(float, __builtin_amdgcn_update_dpp(0, __builtin_bit_cast(int, xs), 0x121, 0xf, 0xf, false));
;       ys += __builtin_bit_cast(float, __builtin_amdgcn_update_dpp(0, __builtin_bit_cast(int, ys), 0x121, 0xf, 0xf, false));
;       if (s > 0) ysel = (kq == s - 1) ? ys : ysel;
;       const float2_t sa2 = {xs, xs};
;       S01 = sa2 * b01 + q01; S23 = sa2 * b23 + q23;
;       float2_t y2 = S01 * r01; y2 = S23 * r23 + y2;
;       ypart = y2.x + y2.y;
	v_pk_mul_f32 v[42:43], v[134:135], v[20:21]
	v_pk_mul_f32 v[46:47], v[122:123], v[20:21]
	v_pk_fma_f32 v[42:43], v[132:133], v[18:19], v[42:43]
	v_pk_mul_f32 v[44:45], v[120:121], v[18:19]
	v_add_f32_e32 v48, v42, v43
	v_pk_fma_f32 v[44:45], v[124:125], v[168:169], v[44:45] op_sel_hi:[1,0,1]
	v_pk_fma_f32 v[46:47], v[126:127], v[168:169], v[46:47] op_sel_hi:[1,0,1]
	v_add_f32_dpp v48, v48, v48 row_ror:8 row_mask:0xf bank_mask:0xf bound_ctrl:1
	v_pk_mul_f32 v[50:51], v[116:117], v[18:19]
	v_pk_fma_f32 v[50:51], v[118:119], v[20:21], v[50:51]
	v_add_f32_dpp v48, v48, v48 row_ror:4 row_mask:0xf bank_mask:0xf bound_ctrl:1
	v_add_f32_e32 v183, v50, v51
	ds_read_b128 v[100:103], v31 offset:1536
	v_add_f32_dpp v48, v48, v48 row_ror:2 row_mask:0xf bank_mask:0xf bound_ctrl:1
	ds_read_b128 v[104:107], v31 offset:5632
	ds_read_b128 v[108:111], v31 offset:9728
	v_add_f32_dpp v48, v48, v48 row_ror:1 row_mask:0xf bank_mask:0xf bound_ctrl:1
	ds_read_b128 v[112:115], v31 offset:13824
	ds_read_b128 v[116:119], v31 offset:17920
	v_pk_fma_f32 v[18:19], v[128:129], v[48:49], v[44:45] op_sel_hi:[1,0,1]
	v_pk_fma_f32 v[20:21], v[130:131], v[48:49], v[46:47] op_sel_hi:[1,0,1]
	s_waitcnt lgkmcnt(7)
	v_pk_mul_f32 v[42:43], v[154:155], v[20:21]
	v_pk_mul_f32 v[46:47], v[142:143], v[20:21]
	v_pk_fma_f32 v[42:43], v[152:153], v[18:19], v[42:43]
	v_pk_mul_f32 v[44:45], v[140:141], v[18:19]
	v_add_f32_e32 v48, v42, v43
	v_pk_fma_f32 v[44:45], v[144:145], v[168:169], v[44:45] op_sel:[0,1,0]
	v_pk_fma_f32 v[46:47], v[146:147], v[168:169], v[46:47] op_sel:[0,1,0]
	v_add_f32_dpp v48, v48, v48 row_ror:8 row_mask:0xf bank_mask:0xf bound_ctrl:1
	v_pk_mul_f32 v[50:51], v[136:137], v[18:19]
	v_pk_fma_f32 v[50:51], v[138:139], v[20:21], v[50:51]
	v_add_f32_dpp v48, v48, v48 row_ror:4 row_mask:0xf bank_mask:0xf bound_ctrl:1
	v_add_f32_e32 v184, v50, v51
	ds_read_b128 v[120:123], v31 offset:1792
	v_add_f32_dpp v48, v48, v48 row_ror:2 row_mask:0xf bank_mask:0xf bound_ctrl:1
	ds_read_b128 v[124:127], v31 offset:5888
	ds_read_b128 v[128:131], v31 offset:9984
	v_add_f32_dpp v48, v48, v48 row_ror:1 row_mask:0xf bank_mask:0xf bound_ctrl:1
	ds_read_b128 v[132:135], v31 offset:14080
	ds_read_b128 v[136:139], v31 offset:18176
	v_pk_fma_f32 v[18:19], v[148:149], v[48:49], v[44:45] op_sel_hi:[1,0,1]
	v_pk_fma_f32 v[20:21], v[150:151], v[48:49], v[46:47] op_sel_hi:[1,0,1]
	s_waitcnt lgkmcnt(5)
	v_pk_mul_f32 v[42:43], v[114:115], v[20:21]
	v_pk_mul_f32 v[46:47], v[102:103], v[20:21]
	v_pk_fma_f32 v[42:43], v[112:113], v[18:19], v[42:43]
	v_pk_mul_f32 v[44:45], v[100:101], v[18:19]
	v_add_f32_e32 v48, v42, v43
	v_pk_fma_f32 v[44:45], v[104:105], v[170:171], v[44:45] op_sel_hi:[1,0,1]
	v_pk_fma_f32 v[46:47], v[106:107], v[170:171], v[46:47] op_sel_hi:[1,0,1]
	v_add_f32_dpp v48, v48, v48 row_ror:8 row_mask:0xf bank_mask:0xf bound_ctrl:1
	v_pk_mul_f32 v[50:51], v[156:157], v[18:19]
	v_pk_fma_f32 v[50:51], v[158:159], v[20:21], v[50:51]
	v_add_f32_dpp v48, v48, v48 row_ror:4 row_mask:0xf bank_mask:0xf bound_ctrl:1
	v_add_f32_e32 v185, v50, v51
	ds_read_b128 v[140:143], v31 offset:2048
	v_add_f32_dpp v48, v48, v48 row_ror:2 row_mask:0xf bank_mask:0xf bound_ctrl:1
	ds_read_b128 v[144:147], v31 offset:6144
	ds_read_b128 v[148:151], v31 offset:10240
	v_add_f32_dpp v48, v48, v48 row_ror:1 row_mask:0xf bank_mask:0xf bound_ctrl:1
	ds_read_b128 v[152:155], v31 offset:14336
	ds_read_b128 v[156:159], v31 offset:18432
	v_pk_fma_f32 v[18:19], v[108:109], v[48:49], v[44:45] op_sel_hi:[1,0,1]
	v_pk_fma_f32 v[20:21], v[110:111], v[48:49], v[46:47] op_sel_hi:[1,0,1]
	s_waitcnt lgkmcnt(5)
	v_pk_mul_f32 v[42:43], v[134:135], v[20:21]
	v_pk_mul_f32 v[46:47], v[122:123], v[20:21]
	v_pk_fma_f32 v[42:43], v[132:133], v[18:19], v[42:43]
	v_pk_mul_f32 v[44:45], v[120:121], v[18:19]
	v_add_f32_e32 v48, v42, v43
	v_pk_fma_f32 v[44:45], v[124:125], v[170:171], v[44:45] op_sel:[0,1,0]
	v_pk_fma_f32 v[46:47], v[126:127], v[170:171], v[46:47] op_sel:[0,1,0]
	v_add_f32_dpp v48, v48, v48 row_ror:8 row_mask:0xf bank_mask:0xf bound_ctrl:1
	v_pk_mul_f32 v[50:51], v[116:117], v[18:19]
	v_pk_fma_f32 v[50:51], v[118:119], v[20:21], v[50:51]
	v_add_f32_dpp v48, v48, v48 row_ror:4 row_mask:0xf bank_mask:0xf bound_ctrl:1
	v_add_f32_e32 v186, v50, v51
	ds_read_b128 v[100:103], v31 offset:2304
	v_add_f32_dpp v48, v48, v48 row_ror:2 row_mask:0xf bank_mask:0xf bound_ctrl:1
	ds_read_b128 v[104:107], v31 offset:6400
	ds_read_b128 v[108:111], v31 offset:10496
	v_add_f32_dpp v48, v48, v48 row_ror:1 row_mask:0xf bank_mask:0xf bound_ctrl:1
	ds_read_b128 v[112:115], v31 offset:14592
	ds_read_b128 v[116:119], v31 offset:18688
	v_pk_fma_f32 v[18:19], v[128:129], v[48:49], v[44:45] op_sel_hi:[1,0,1]
	v_pk_fma_f32 v[20:21], v[130:131], v[48:49], v[46:47] op_sel_hi:[1,0,1]
	s_waitcnt lgkmcnt(5)
	v_pk_mul_f32 v[42:43], v[154:155], v[20:21]
	v_pk_mul_f32 v[46:47], v[142:143], v[20:21]
	v_pk_fma_f32 v[42:43], v[152:153], v[18:19], v[42:43]
	v_pk_mul_f32 v[44:45], v[140:141], v[18:19]
	v_add_f32_e32 v48, v42, v43
	v_pk_fma_f32 v[44:45], v[144:145], v[172:173], v[44:45] op_sel_hi:[1,0,1]
	v_pk_fma_f32 v[46:47], v[146:147], v[172:173], v[46:47] op_sel_hi:[1,0,1]
	v_add_f32_dpp v48, v48, v48 row_ror:8 row_mask:0xf bank_mask:0xf bound_ctrl:1
	v_pk_mul_f32 v[50:51], v[136:137], v[18:19]
	v_pk_fma_f32 v[50:51], v[138:139], v[20:21], v[50:51]
	v_add_f32_dpp v48, v48, v48 row_ror:4 row_mask:0xf bank_mask:0xf bound_ctrl:1
	v_add_f32_e32 v187, v50, v51
	ds_read_b128 v[120:123], v31 offset:2560
	v_add_f32_dpp v48, v48, v48 row_ror:2 row_mask:0xf bank_mask:0xf bound_ctrl:1
	ds_read_b128 v[124:127], v31 offset:6656
	ds_read_b128 v[128:131], v31 offset:10752
	v_add_f32_dpp v48, v48, v48 row_ror:1 row_mask:0xf bank_mask:0xf bound_ctrl:1
	ds_read_b128 v[132:135], v31 offset:14848
	ds_read_b128 v[136:139], v31 offset:18944
	v_pk_fma_f32 v[18:19], v[148:149], v[48:49], v[44:45] op_sel_hi:[1,0,1]
	v_pk_fma_f32 v[20:21], v[150:151], v[48:49], v[46:47] op_sel_hi:[1,0,1]
	s_waitcnt lgkmcnt(5)
; DI void phase_scan(const Params& p, char* smem) {
;     ...
;       const float4 fw = fwv[s % 3], fk = fkv[s % 3], fb = fbv[s % 3], fa = fav[s % 3], fr = frv[s % 3];
;       const float vv = vvv[s % 3];
;       const float2_t a01 = {fa.x, fa.y}, a23 = {fa.z, fa.w};
;       const float2_t w01 = {fw.x, fw.y}, w23 = {fw.z, fw.w}, k01 = {fk.x, fk.y}, k23 = {fk.z, fk.w}, b01 = {fb.x, fb.y}, b23 = {fb.z, fb.w};
;       const float2_t r01 = {fr.x, fr.y}, r23 = {fr.z, fr.w};
;       const float2_t vv2 = {vv, vv};
;       if (s + 2 < CH) {
;         constexpr int dummy = 0; (void)dummy;
;         const int q = (s + 2) % 3;
;         fwv[q] = *(const float4*)(bl + 0 * CH * 64 + (s + 2) * 64); fkv[q] = *(const float4*)(bl + 1 * CH * 64 + (s + 2) * 64); fbv[q] = *(const float4*)(bl + 2 * CH * 64 + (s + 2) * 64);
;         fav[q] = *(const float4*)(bl + 3 * CH * 64 + (s + 2) * 64); frv[q] = *(const float4*)(bl + 4 * CH * 64 + (s + 2) * 64); vvv[q] = bv[(s + 2) * 16];
;       }
;       float2_t t2 = S01 * a01; t2 = S23 * a23 + t2;
;       const float2_t q01 = S01 * w01 + vv2 * k01, q23 = S23 * w23 + vv2 * k23;
;       float xs = t2.x + t2.y, ys = ypart;
;       xs += __builtin_bit_cast(float, __builtin_amdgcn_update_dpp(0, __builtin_bit_cast(int, xs), 0x128, 0xf, 0xf, false));
;       ys += __builtin_bit_cast(float, __builtin_amdgcn_update_dpp(0, __builtin_bit_cast(int, ys), 0x128, 0xf, 0xf, false));
;       xs += __builtin_bit_cast(float, __builtin_amdgcn_update_dpp(0, __builtin_bit_cast(int, xs), 0x124, 0xf, 0xf, false));
;       ys += __builtin_bit_cast(float, __builtin_amdgcn_update_dpp(0, __builtin_bit_cast(int, ys), 0x124, 0xf, 0xf, false));
;       xs += __builtin_bit_cast(float, __builtin_amdgcn_update_dpp(0, __builtin_bit_cast(int, xs), 0x122, 0xf, 0xf, false));
;       ys += __builtin_bit_cast(float, __builtin_amdgcn_update_dpp(0, __builtin_bit_cast(int, ys), 0x122, 0xf, 0xf, false));
;       xs += __builtin_bit_cast(float, __builtin_amdgcn_update_dpp(0, __builtin_bit_cast(int, xs), 0x121, 0xf, 0xf, false));
;       ys += __builtin_bit_cast(float, __builtin_amdgcn_update_dpp(0, __builtin_bit_cast(int, ys), 0x121, 0xf, 0xf, false));
;       if (s > 0) ysel = (kq == s - 1) ? ys : ysel;
;       const float2_t sa2 = {xs, xs};
;       S01 = sa2 * b01 + q01; S23 = sa2 * b23 + q23;
;       float2_t y2 = S01 * r01; y2 = S23 * r23 + y2;
;       ypart = y2.x + y2.y;
	v_pk_mul_f32 v[42:43], v[114:115], v[20:21]
	v_pk_mul_f32 v[46:47], v[102:103], v[20:21]
	v_pk_fma_f32 v[42:43], v[112:113], v[18:19], v[42:43]
	v_pk_mul_f32 v[44:45], v[100:101], v[18:19]
	v_add_f32_e32 v48, v42, v43
	v_pk_fma_f32 v[44:45], v[104:105], v[172:173], v[44:45] op_sel:[0,1,0]
	v_pk_fma_f32 v[46:47], v[106:107], v[172:173], v[46:47] op_sel:[0,1,0]
	v_add_f32_dpp v48, v48, v48 row_ror:8 row_mask:0xf bank_mask:0xf bound_ctrl:1
	v_pk_mul_f32 v[50:51], v[156:157], v[18:19]
	v_pk_fma_f32 v[50:51], v[158:159], v[20:21], v[50:51]
	v_add_f32_dpp v48, v48, v48 row_ror:4 row_mask:0xf bank_mask:0xf bound_ctrl:1
	v_add_f32_e32 v188, v50, v51
	ds_read_b128 v[140:143], v31 offset:2816
	v_add_f32_dpp v48, v48, v48 row_ror:2 row_mask:0xf bank_mask:0xf bound_ctrl:1
	ds_read_b128 v[144:147], v31 offset:6912
	ds_read_b128 v[148:151], v31 offset:11008
	v_add_f32_dpp v48, v48, v48 row_ror:1 row_mask:0xf bank_mask:0xf bound_ctrl:1
	ds_read_b128 v[152:155], v31 offset:15104
	ds_read_b128 v[156:159], v31 offset:19200
	v_pk_fma_f32 v[18:19], v[108:109], v[48:49], v[44:45] op_sel_hi:[1,0,1]
	v_pk_fma_f32 v[20:21], v[110:111], v[48:49], v[46:47] op_sel_hi:[1,0,1]
	s_waitcnt lgkmcnt(5)
	v_pk_mul_f32 v[42:43], v[134:135], v[20:21]
	v_pk_mul_f32 v[46:47], v[122:123], v[20:21]
	v_pk_fma_f32 v[42:43], v[132:133], v[18:19], v[42:43]
	v_pk_mul_f32 v[44:45], v[120:121], v[18:19]
	v_add_f32_e32 v48, v42, v43
	v_pk_fma_f32 v[44:45], v[124:125], v[174:175], v[44:45] op_sel_hi:[1,0,1]
	v_pk_fma_f32 v[46:47], v[126:127], v[174:175], v[46:47] op_sel_hi:[1,0,1]
	v_add_f32_dpp v48, v48, v48 row_ror:8 row_mask:0xf bank_mask:0xf bound_ctrl:1
	v_pk_mul_f32 v[50:51], v[116:117], v[18:19]
	v_pk_fma_f32 v[50:51], v[118:119], v[20:21], v[50:51]
	v_add_f32_dpp v48, v48, v48 row_ror:4 row_mask:0xf bank_mask:0xf bound_ctrl:1
	v_add_f32_e32 v189, v50, v51
	ds_read_b128 v[100:103], v31 offset:3072
	v_add_f32_dpp v48, v48, v48 row_ror:2 row_mask:0xf bank_mask:0xf bound_ctrl:1
	ds_read_b128 v[104:107], v31 offset:7168
	ds_read_b128 v[108:111], v31 offset:11264
	v_add_f32_dpp v48, v48, v48 row_ror:1 row_mask:0xf bank_mask:0xf bound_ctrl:1
	ds_read_b128 v[112:115], v31 offset:15360
	ds_read_b128 v[116:119], v31 offset:19456
	v_pk_fma_f32 v[18:19], v[128:129], v[48:49], v[44:45] op_sel_hi:[1,0,1]
	v_pk_fma_f32 v[20:21], v[130:131], v[48:49], v[46:47] op_sel_hi:[1,0,1]
	s_waitcnt lgkmcnt(5)
	v_pk_mul_f32 v[42:43], v[154:155], v[20:21]
	v_pk_mul_f32 v[46:47], v[142:143], v[20:21]
	v_pk_fma_f32 v[42:43], v[152:153], v[18:19], v[42:43]
	v_pk_mul_f32 v[44:45], v[140:141], v[18:19]
	v_add_f32_e32 v48, v42, v43
	v_pk_fma_f32 v[44:45], v[144:145], v[174:175], v[44:45] op_sel:[0,1,0]
	v_pk_fma_f32 v[46:47], v[146:147], v[174:175], v[46:47] op_sel:[0,1,0]
	v_add_f32_dpp v48, v48, v48 row_ror:8 row_mask:0xf bank_mask:0xf bound_ctrl:1
	v_pk_mul_f32 v[50:51], v[136:137], v[18:19]
	v_pk_fma_f32 v[50:51], v[138:139], v[20:21], v[50:51]
	v_add_f32_dpp v48, v48, v48 row_ror:4 row_mask:0xf bank_mask:0xf bound_ctrl:1
	v_add_f32_e32 v190, v50, v51
	ds_read_b128 v[120:123], v31 offset:3328
	v_add_f32_dpp v48, v48, v48 row_ror:2 row_mask:0xf bank_mask:0xf bound_ctrl:1
	ds_read_b128 v[124:127], v31 offset:7424
	ds_read_b128 v[128:131], v31 offset:11520
	v_add_f32_dpp v48, v48, v48 row_ror:1 row_mask:0xf bank_mask:0xf bound_ctrl:1
	ds_read_b128 v[132:135], v31 offset:15616
	ds_read_b128 v[136:139], v31 offset:19712
	v_pk_fma_f32 v[18:19], v[148:149], v[48:49], v[44:45] op_sel_hi:[1,0,1]
	v_pk_fma_f32 v[20:21], v[150:151], v[48:49], v[46:47] op_sel_hi:[1,0,1]
	s_waitcnt lgkmcnt(5)
	v_pk_mul_f32 v[42:43], v[114:115], v[20:21]
	v_pk_mul_f32 v[46:47], v[102:103], v[20:21]
	v_pk_fma_f32 v[42:43], v[112:113], v[18:19], v[42:43]
	v_pk_mul_f32 v[44:45], v[100:101], v[18:19]
	v_add_f32_e32 v48, v42, v43
	v_pk_fma_f32 v[44:45], v[104:105], v[176:177], v[44:45] op_sel_hi:[1,0,1]
	v_pk_fma_f32 v[46:47], v[106:107], v[176:177], v[46:47] op_sel_hi:[1,0,1]
	v_add_f32_dpp v48, v48, v48 row_ror:8 row_mask:0xf bank_mask:0xf bound_ctrl:1
	v_pk_mul_f32 v[50:51], v[156:157], v[18:19]
	v_pk_fma_f32 v[50:51], v[158:159], v[20:21], v[50:51]
	v_add_f32_dpp v48, v48, v48 row_ror:4 row_mask:0xf bank_mask:0xf bound_ctrl:1
	v_add_f32_e32 v191, v50, v51
	ds_read_b128 v[140:143], v31 offset:3584
	v_add_f32_dpp v48, v48, v48 row_ror:2 row_mask:0xf bank_mask:0xf bound_ctrl:1
	ds_read_b128 v[144:147], v31 offset:7680
	ds_read_b128 v[148:151], v31 offset:11776
	v_add_f32_dpp v48, v48, v48 row_ror:1 row_mask:0xf bank_mask:0xf bound_ctrl:1
	ds_read_b128 v[152:155], v31 offset:15872
	ds_read_b128 v[156:159], v31 offset:19968
	v_pk_fma_f32 v[18:19], v[108:109], v[48:49], v[44:45] op_sel_hi:[1,0,1]
	v_pk_fma_f32 v[20:21], v[110:111], v[48:49], v[46:47] op_sel_hi:[1,0,1]
	s_waitcnt lgkmcnt(5)
	v_pk_mul_f32 v[42:43], v[134:135], v[20:21]
	v_pk_mul_f32 v[46:47], v[122:123], v[20:21]
	v_pk_fma_f32 v[42:43], v[132:133], v[18:19], v[42:43]
	v_pk_mul_f32 v[44:45], v[120:121], v[18:19]
	v_add_f32_e32 v48, v42, v43
	v_pk_fma_f32 v[44:45], v[124:125], v[176:177], v[44:45] op_sel:[0,1,0]
	v_pk_fma_f32 v[46:47], v[126:127], v[176:177], v[46:47] op_sel:[0,1,0]
	v_add_f32_dpp v48, v48, v48 row_ror:8 row_mask:0xf bank_mask:0xf bound_ctrl:1
	v_pk_mul_f32 v[50:51], v[116:117], v[18:19]
	v_pk_fma_f32 v[50:51], v[118:119], v[20:21], v[50:51]
	v_add_f32_dpp v48, v48, v48 row_ror:4 row_mask:0xf bank_mask:0xf bound_ctrl:1
	v_add_f32_e32 v192, v50, v51
	ds_read_b128 v[100:103], v31 offset:3840
	v_add_f32_dpp v48, v48, v48 row_ror:2 row_mask:0xf bank_mask:0xf bound_ctrl:1
	ds_read_b128 v[104:107], v31 offset:7936
	ds_read_b128 v[108:111], v31 offset:12032
	v_add_f32_dpp v48, v48, v48 row_ror:1 row_mask:0xf bank_mask:0xf bound_ctrl:1
	ds_read_b128 v[112:115], v31 offset:16128
	ds_read_b128 v[116:119], v31 offset:20224
	v_pk_fma_f32 v[18:19], v[128:129], v[48:49], v[44:45] op_sel_hi:[1,0,1]
	v_pk_fma_f32 v[20:21], v[130:131], v[48:49], v[46:47] op_sel_hi:[1,0,1]
	s_waitcnt lgkmcnt(5)
; DI u16 f2bf(float a) { return (u16)(pack2(a, 0.f) & 0xffffu); }
; DI void phase_scan(const Params& p, char* smem) {
;     ...
;       float2_t t2 = S01 * a01; t2 = S23 * a23 + t2;
;       const float2_t q01 = S01 * w01 + vv2 * k01, q23 = S23 * w23 + vv2 * k23;
;       float xs = t2.x + t2.y, ys = ypart;
;       xs += __builtin_bit_cast(float, __builtin_amdgcn_update_dpp(0, __builtin_bit_cast(int, xs), 0x128, 0xf, 0xf, false));
;       ys += __builtin_bit_cast(float, __builtin_amdgcn_update_dpp(0, __builtin_bit_cast(int, ys), 0x128, 0xf, 0xf, false));
;       xs += __builtin_bit_cast(float, __builtin_amdgcn_update_dpp(0, __builtin_bit_cast(int, xs), 0x124, 0xf, 0xf, false));
;       ys += __builtin_bit_cast(float, __builtin_amdgcn_update_dpp(0, __builtin_bit_cast(int, ys), 0x124, 0xf, 0xf, false));
;       xs += __builtin_bit_cast(float, __builtin_amdgcn_update_dpp(0, __builtin_bit_cast(int, xs), 0x122, 0xf, 0xf, false));
;       ys += __builtin_bit_cast(float, __builtin_amdgcn_update_dpp(0, __builtin_bit_cast(int, ys), 0x122, 0xf, 0xf, false));
;       xs += __builtin_bit_cast(float, __builtin_amdgcn_update_dpp(0, __builtin_bit_cast(int, xs), 0x121, 0xf, 0xf, false));
;       ys += __builtin_bit_cast(float, __builtin_amdgcn_update_dpp(0, __builtin_bit_cast(int, ys), 0x121, 0xf, 0xf, false));
;       if (s > 0) ysel = (kq == s - 1) ? ys : ysel;
;       const float2_t sa2 = {xs, xs};
;       S01 = sa2 * b01 + q01; S23 = sa2 * b23 + q23;
;       float2_t y2 = S01 * r01; y2 = S23 * r23 + y2;
;       ypart = y2.x + y2.y;
;     }
;     { const float yl = rowsum16(ypart); ysel = (kq == CH - 1) ? yl : ysel; }
;     Y[(size_t)(rowbase + rstep * kq) * 256 + h * 64 + vrow] = f2bf(ysel);
;     if (c + 1 < NCH) SCAN_LSTORE((c + 1) & 1);
	v_pk_mul_f32 v[42:43], v[154:155], v[20:21]
	v_pk_mul_f32 v[46:47], v[142:143], v[20:21]
	v_pk_fma_f32 v[42:43], v[152:153], v[18:19], v[42:43]
	v_pk_mul_f32 v[44:45], v[140:141], v[18:19]
	v_add_f32_e32 v48, v42, v43
	v_pk_fma_f32 v[44:45], v[144:145], v[178:179], v[44:45] op_sel_hi:[1,0,1]
	v_pk_fma_f32 v[46:47], v[146:147], v[178:179], v[46:47] op_sel_hi:[1,0,1]
	v_add_f32_dpp v48, v48, v48 row_ror:8 row_mask:0xf bank_mask:0xf bound_ctrl:1
	v_pk_mul_f32 v[50:51], v[136:137], v[18:19]
	v_pk_fma_f32 v[50:51], v[138:139], v[20:21], v[50:51]
	v_add_f32_dpp v48, v48, v48 row_ror:4 row_mask:0xf bank_mask:0xf bound_ctrl:1
	v_add_f32_e32 v193, v50, v51
	s_nop 0
	v_add_f32_dpp v48, v48, v48 row_ror:2 row_mask:0xf bank_mask:0xf bound_ctrl:1
	s_nop 1
	v_add_f32_dpp v48, v48, v48 row_ror:1 row_mask:0xf bank_mask:0xf bound_ctrl:1
	v_pk_fma_f32 v[18:19], v[148:149], v[48:49], v[44:45] op_sel_hi:[1,0,1]
	v_pk_fma_f32 v[20:21], v[150:151], v[48:49], v[46:47] op_sel_hi:[1,0,1]
	s_waitcnt lgkmcnt(0)
	v_pk_mul_f32 v[42:43], v[114:115], v[20:21]
	v_pk_mul_f32 v[46:47], v[102:103], v[20:21]
	v_pk_fma_f32 v[42:43], v[112:113], v[18:19], v[42:43]
	v_pk_mul_f32 v[44:45], v[100:101], v[18:19]
	v_add_f32_e32 v48, v42, v43
	v_pk_fma_f32 v[44:45], v[104:105], v[178:179], v[44:45] op_sel:[0,1,0]
	v_pk_fma_f32 v[46:47], v[106:107], v[178:179], v[46:47] op_sel:[0,1,0]
	v_add_f32_dpp v48, v48, v48 row_ror:8 row_mask:0xf bank_mask:0xf bound_ctrl:1
	v_pk_mul_f32 v[50:51], v[156:157], v[18:19]
	v_pk_fma_f32 v[50:51], v[158:159], v[20:21], v[50:51]
	v_add_f32_dpp v48, v48, v48 row_ror:4 row_mask:0xf bank_mask:0xf bound_ctrl:1
	v_add_f32_e32 v194, v50, v51
	s_nop 0
	v_add_f32_dpp v48, v48, v48 row_ror:2 row_mask:0xf bank_mask:0xf bound_ctrl:1
	s_nop 1
	v_add_f32_dpp v48, v48, v48 row_ror:1 row_mask:0xf bank_mask:0xf bound_ctrl:1
	v_pk_fma_f32 v[18:19], v[108:109], v[48:49], v[44:45] op_sel_hi:[1,0,1]
	v_pk_fma_f32 v[20:21], v[110:111], v[48:49], v[46:47] op_sel_hi:[1,0,1]
	v_pk_mul_f32 v[50:51], v[116:117], v[18:19]
	v_pk_fma_f32 v[50:51], v[118:119], v[20:21], v[50:51]
	v_add_f32_e32 v195, v50, v51
	v_and_b32_e32 v52, 32, v2
	v_and_b32_e32 v53, 16, v2
	v_cmp_ne_u32_e64 s[4:5], 0, v52
	v_cmp_ne_u32_e64 s[6:7], 0, v53
	v_and_b32_e32 v52, 8, v2
	v_and_b32_e32 v53, 4, v2
	v_cmp_ne_u32_e64 s[8:9], 0, v52
	v_cmp_ne_u32_e64 s[10:11], 0, v53
	v_cndmask_b32_e64 v52, v188, v180, s[4:5]
	v_cndmask_b32_e64 v53, v180, v188, s[4:5]
	v_cndmask_b32_e64 v54, v189, v181, s[4:5]
	v_cndmask_b32_e64 v55, v181, v189, s[4:5]
	v_cndmask_b32_e64 v56, v190, v182, s[4:5]
	v_cndmask_b32_e64 v57, v182, v190, s[4:5]
	v_cndmask_b32_e64 v58, v191, v183, s[4:5]
	v_cndmask_b32_e64 v59, v183, v191, s[4:5]
	v_add_f32_dpp v60, v52, v53 row_ror:8 row_mask:0xf bank_mask:0xf bound_ctrl:1
	v_add_f32_dpp v61, v54, v55 row_ror:8 row_mask:0xf bank_mask:0xf bound_ctrl:1
	v_add_f32_dpp v62, v56, v57 row_ror:8 row_mask:0xf bank_mask:0xf bound_ctrl:1
	v_add_f32_dpp v63, v58, v59 row_ror:8 row_mask:0xf bank_mask:0xf bound_ctrl:1
	v_cndmask_b32_e64 v52, v192, v184, s[4:5]
	v_cndmask_b32_e64 v53, v184, v192, s[4:5]
	v_cndmask_b32_e64 v54, v193, v185, s[4:5]
	v_cndmask_b32_e64 v55, v185, v193, s[4:5]
	v_cndmask_b32_e64 v56, v194, v186, s[4:5]
	v_cndmask_b32_e64 v57, v186, v194, s[4:5]
	v_cndmask_b32_e64 v58, v195, v187, s[4:5]
	v_cndmask_b32_e64 v59, v187, v195, s[4:5]
	v_add_f32_dpp v64, v52, v53 row_ror:8 row_mask:0xf bank_mask:0xf bound_ctrl:1
	v_add_f32_dpp v65, v54, v55 row_ror:8 row_mask:0xf bank_mask:0xf bound_ctrl:1
	v_add_f32_dpp v66, v56, v57 row_ror:8 row_mask:0xf bank_mask:0xf bound_ctrl:1
	v_add_f32_dpp v67, v58, v59 row_ror:8 row_mask:0xf bank_mask:0xf bound_ctrl:1
	v_cndmask_b32_e64 v52, v64, v60, s[6:7]
	v_cndmask_b32_e64 v53, v60, v64, s[6:7]
	v_cndmask_b32_e64 v54, v65, v61, s[6:7]
	v_cndmask_b32_e64 v55, v61, v65, s[6:7]
	v_cndmask_b32_e64 v56, v66, v62, s[6:7]
	v_cndmask_b32_e64 v57, v62, v66, s[6:7]
	v_cndmask_b32_e64 v58, v67, v63, s[6:7]
	v_cndmask_b32_e64 v59, v63, v67, s[6:7]
	v_add_f32_dpp v68, v52, v53 row_half_mirror row_mask:0xf bank_mask:0xf bound_ctrl:1
	v_add_f32_dpp v69, v54, v55 row_half_mirror row_mask:0xf bank_mask:0xf bound_ctrl:1
	v_add_f32_dpp v70, v56, v57 row_half_mirror row_mask:0xf bank_mask:0xf bound_ctrl:1
	v_add_f32_dpp v71, v58, v59 row_half_mirror row_mask:0xf bank_mask:0xf bound_ctrl:1
	v_cndmask_b32_e64 v52, v70, v68, s[8:9]
	v_cndmask_b32_e64 v53, v68, v70, s[8:9]
	v_cndmask_b32_e64 v54, v71, v69, s[8:9]
	v_cndmask_b32_e64 v55, v69, v71, s[8:9]
	v_add_f32_dpp v72, v52, v53 quad_perm:[3,2,1,0] row_mask:0xf bank_mask:0xf bound_ctrl:1
	v_add_f32_dpp v73, v54, v55 quad_perm:[3,2,1,0] row_mask:0xf bank_mask:0xf bound_ctrl:1
	v_cndmask_b32_e64 v52, v73, v72, s[10:11]
	v_cndmask_b32_e64 v53, v72, v73, s[10:11]
	s_nop 1
	v_add_f32_dpp v31, v52, v53 quad_perm:[1,0,3,2] row_mask:0xf bank_mask:0xf bound_ctrl:1
	v_cvt_pk_bf16_f32 v32, v31, s0
	v_ashrrev_i32_e32 v31, 31, v30
	v_lshlrev_b64 v[30:31], 9, v[30:31]
	v_lshl_add_u64 v[30:31], v[16:17], 0, v[30:31]
	flat_store_short v[30:31], v32
	s_cbranch_vccnz .LBB0_507
	s_bitcmp1_b32 s96, 0
	s_cselect_b32 s46, 0x5400, 0
	s_waitcnt vmcnt(0)
	v_lshlrev_b32_e32 v30, 16, v4
	v_and_b32_e32 v31, 0xffff0000, v4
	v_lshlrev_b32_e32 v32, 16, v5
	v_and_b32_e32 v33, 0xffff0000, v5
	v_add_u32_e32 v34, s46, v26
	v_pk_add_f32 v[30:31], v[30:31], 1.0 op_sel_hi:[1,0] neg_lo:[1,0] neg_hi:[1,0]
	v_pk_add_f32 v[32:33], v[32:33], 1.0 op_sel_hi:[1,0] neg_lo:[1,0] neg_hi:[1,0]
	ds_write_b128 v34, v[30:33]
	v_lshlrev_b32_e32 v30, 16, v6
	v_and_b32_e32 v31, 0xffff0000, v6
	v_lshlrev_b32_e32 v32, 16, v7
	v_and_b32_e32 v33, 0xffff0000, v7
	ds_write_b128 v34, v[30:33] offset:4096
	v_lshlrev_b32_e32 v30, 16, v8
	v_and_b32_e32 v31, 0xffff0000, v8
	v_lshlrev_b32_e32 v32, 16, v9
	v_and_b32_e32 v33, 0xffff0000, v9
	ds_write_b128 v34, v[30:33] offset:8192
	v_lshlrev_b32_e32 v30, 16, v10
	v_and_b32_e32 v31, 0xffff0000, v10
	v_lshlrev_b32_e32 v32, 16, v11
	v_and_b32_e32 v33, 0xffff0000, v11
	ds_write_b128 v34, v[30:33] offset:12288
	v_lshlrev_b32_e32 v30, 16, v12
	v_and_b32_e32 v31, 0xffff0000, v12
	v_lshlrev_b32_e32 v32, 16, v13
	v_and_b32_e32 v33, 0xffff0000, v13
	ds_write_b128 v34, v[30:33] offset:16384
	v_lshlrev_b32_e32 v30, 16, v27
	v_add_u32_e32 v31, s46, v28
	ds_write_b32 v31, v30 offset:20480
	s_branch .LBB0_507
